# same as previous stack (without early x1-copy stores) plus a bounded-outstanding wait in the P0 GEMV second load burst
# speedup vs baseline: 1.0016x; 1.0016x over previous
.LBB0_13:
	v_lshlrev_b32_e32 v34, 2, v0
	v_mov_b32_e32 v35, 0
	v_lshl_add_u64 v[2:3], s[38:39], 0, v[34:35]
	global_load_dword v8, v34, s[38:39]
	global_load_dword v9, v34, s[38:39] offset:2048
	v_add_co_u32_e32 v4, vcc, 0x1000, v2
	s_movk_i32 s1, 0x6000
	s_nop 0
	v_addc_co_u32_e32 v5, vcc, 0, v3, vcc
	global_load_dword v10, v[4:5], off
	global_load_dword v11, v[4:5], off offset:2048
	v_add_co_u32_e32 v4, vcc, 0x2000, v2
	s_lshl_b32 s6, s0, 5
	s_nop 0
	v_addc_co_u32_e32 v5, vcc, 0, v3, vcc
	global_load_dword v12, v[4:5], off
	global_load_dword v13, v[4:5], off offset:2048
	v_add_co_u32_e32 v4, vcc, 0x3000, v2
	s_ashr_i32 s7, s6, 31
	s_nop 0
	v_addc_co_u32_e32 v5, vcc, 0, v3, vcc
	global_load_dword v14, v[4:5], off
	global_load_dword v15, v[4:5], off offset:2048
	v_add_co_u32_e32 v4, vcc, 0x4000, v2
	v_and_b32_e32 v48, 31, v0
	s_nop 0
	v_addc_co_u32_e32 v5, vcc, 0, v3, vcc
	global_load_dword v16, v[4:5], off
	global_load_dword v17, v[4:5], off offset:2048
	v_add_co_u32_e32 v4, vcc, 0x5000, v2
	v_lshlrev_b32_e32 v34, 2, v48
	s_nop 0
	v_addc_co_u32_e32 v5, vcc, 0, v3, vcc
	global_load_dword v18, v[4:5], off
	v_add_co_u32_e32 v6, vcc, 0x6000, v2
	global_load_dword v19, v[4:5], off offset:2048
	s_nop 0
	v_addc_co_u32_e32 v7, vcc, 0, v3, vcc
	global_load_dword v20, v[6:7], off
	v_add_co_u32_e32 v2, vcc, 0x7000, v2
	global_load_dword v6, v[6:7], off offset:2048
	s_nop 0
	v_addc_co_u32_e32 v3, vcc, 0, v3, vcc
	global_load_dword v7, v[2:3], off
	s_mov_b64 s[38:39], 0
	global_load_dword v2, v[2:3], off offset:2048
	v_lshl_add_u32 v3, v0, 5, 0
	v_add_u32_e32 v21, 0x4000, v3
	v_mov_b32_e32 v4, s40
	v_mov_b32_e32 v5, s41
	v_lshrrev_b32_e32 v244, 5, v1
	v_lshl_or_b32 v244, s99, 7, v244
	s_movk_i32 s32, 0x6000
	v_or_b32_e32 v245, s6, v48
	v_mad_u64_u32 v[246:247], s[96:97], v244, s32, v[4:5]
	v_lshlrev_b32_e32 v248, 2, v245
	v_and_b32_e32 v245, 0x3ff, v245
	v_lshl_add_u64 v[246:247], s[6:7], 2, v[246:247]
	v_lshlrev_b32_e32 v245, 2, v245
	v_lshl_add_u64 v[240:241], v[246:247], 0, v[34:35]
	s_ashr_i32 s32, s0, 5
	v_readlane_b32 s96, v250, 0
	v_readlane_b32 s97, v250, 1
	s_nop 3
	s_cmp_eq_u32 s32, 4
	s_cselect_b32 s96, s22, s96
	s_cselect_b32 s97, s23, s97
	s_cmp_eq_u32 s32, 2
	s_cselect_b32 s96, s46, s96
	s_cselect_b32 s97, s47, s97
	s_cmp_eq_u32 s32, 1
	s_cselect_b32 s96, s44, s96
	s_cselect_b32 s97, s45, s97
	global_load_dword v242, v248, s[42:43]
	global_load_dword v243, v245, s[96:97]
	s_nop 1
	s_mov_b32 s96, 0xc000
	s_mov_b32 s97, 0
	global_load_dword v176, v[240:241], off nt
	v_lshl_add_u64 v[240:241], v[240:241], 0, s[96:97]
	global_load_dword v177, v[240:241], off nt
	v_lshl_add_u64 v[240:241], v[240:241], 0, s[96:97]
	global_load_dword v178, v[240:241], off nt
	v_lshl_add_u64 v[240:241], v[240:241], 0, s[96:97]
	global_load_dword v179, v[240:241], off nt
	v_lshl_add_u64 v[240:241], v[240:241], 0, s[96:97]
	global_load_dword v180, v[240:241], off nt
	v_lshl_add_u64 v[240:241], v[240:241], 0, s[96:97]
	global_load_dword v181, v[240:241], off nt
	v_lshl_add_u64 v[240:241], v[240:241], 0, s[96:97]
	global_load_dword v182, v[240:241], off nt
	v_lshl_add_u64 v[240:241], v[240:241], 0, s[96:97]
	global_load_dword v183, v[240:241], off nt
	v_lshl_add_u64 v[240:241], v[240:241], 0, s[96:97]
	global_load_dword v184, v[240:241], off nt
	v_lshl_add_u64 v[240:241], v[240:241], 0, s[96:97]
	global_load_dword v185, v[240:241], off nt
	v_lshl_add_u64 v[240:241], v[240:241], 0, s[96:97]
	global_load_dword v186, v[240:241], off nt
	v_lshl_add_u64 v[240:241], v[240:241], 0, s[96:97]
	global_load_dword v187, v[240:241], off nt
	v_lshl_add_u64 v[240:241], v[240:241], 0, s[96:97]
	global_load_dword v188, v[240:241], off nt
	v_lshl_add_u64 v[240:241], v[240:241], 0, s[96:97]
	global_load_dword v189, v[240:241], off nt
	v_lshl_add_u64 v[240:241], v[240:241], 0, s[96:97]
	global_load_dword v190, v[240:241], off nt
	v_lshl_add_u64 v[240:241], v[240:241], 0, s[96:97]
	global_load_dword v191, v[240:241], off nt
	v_lshl_add_u64 v[240:241], v[240:241], 0, s[96:97]
	global_load_dword v192, v[240:241], off nt
	v_lshl_add_u64 v[240:241], v[240:241], 0, s[96:97]
	global_load_dword v193, v[240:241], off nt
	v_lshl_add_u64 v[240:241], v[240:241], 0, s[96:97]
	global_load_dword v194, v[240:241], off nt
	v_lshl_add_u64 v[240:241], v[240:241], 0, s[96:97]
	global_load_dword v195, v[240:241], off nt
	v_lshl_add_u64 v[240:241], v[240:241], 0, s[96:97]
	global_load_dword v196, v[240:241], off nt
	v_lshl_add_u64 v[240:241], v[240:241], 0, s[96:97]
	global_load_dword v197, v[240:241], off nt
	v_lshl_add_u64 v[240:241], v[240:241], 0, s[96:97]
	global_load_dword v198, v[240:241], off nt
	v_lshl_add_u64 v[240:241], v[240:241], 0, s[96:97]
	global_load_dword v199, v[240:241], off nt
	v_lshl_add_u64 v[240:241], v[240:241], 0, s[96:97]
	global_load_dword v200, v[240:241], off nt
	v_lshl_add_u64 v[240:241], v[240:241], 0, s[96:97]
	global_load_dword v201, v[240:241], off nt
	v_lshl_add_u64 v[240:241], v[240:241], 0, s[96:97]
	global_load_dword v202, v[240:241], off nt
	v_lshl_add_u64 v[240:241], v[240:241], 0, s[96:97]
	global_load_dword v203, v[240:241], off nt
	v_lshl_add_u64 v[240:241], v[240:241], 0, s[96:97]
	global_load_dword v204, v[240:241], off nt
	v_lshl_add_u64 v[240:241], v[240:241], 0, s[96:97]
	global_load_dword v205, v[240:241], off nt
	v_lshl_add_u64 v[240:241], v[240:241], 0, s[96:97]
	global_load_dword v206, v[240:241], off nt
	v_lshl_add_u64 v[240:241], v[240:241], 0, s[96:97]
	global_load_dword v207, v[240:241], off nt
	v_lshl_add_u64 v[240:241], v[240:241], 0, s[96:97]
	global_load_dword v208, v[240:241], off nt
	v_lshl_add_u64 v[240:241], v[240:241], 0, s[96:97]
	global_load_dword v209, v[240:241], off nt
	v_lshl_add_u64 v[240:241], v[240:241], 0, s[96:97]
	global_load_dword v210, v[240:241], off nt
	v_lshl_add_u64 v[240:241], v[240:241], 0, s[96:97]
	global_load_dword v211, v[240:241], off nt
	v_lshl_add_u64 v[240:241], v[240:241], 0, s[96:97]
	global_load_dword v212, v[240:241], off nt
	v_lshl_add_u64 v[240:241], v[240:241], 0, s[96:97]
	global_load_dword v213, v[240:241], off nt
	v_lshl_add_u64 v[240:241], v[240:241], 0, s[96:97]
	global_load_dword v214, v[240:241], off nt
	v_lshl_add_u64 v[240:241], v[240:241], 0, s[96:97]
	global_load_dword v215, v[240:241], off nt
	v_lshl_add_u64 v[240:241], v[240:241], 0, s[96:97]
	s_mov_b32 s3, 0x18000
	s_mov_b32 s26, 0x48000
	s_mov_b32 s27, 0x54000
	s_mov_b32 s28, 0x60000
	s_mov_b32 s29, 0x6c000
	s_mov_b32 s30, 0x78000
	s_mov_b32 s31, 0x84000
	s_mov_b32 s40, 0x90000
	s_mov_b32 s41, 0x9c000
	s_mov_b32 s72, 0xa8000
	s_mov_b32 s73, 0xb4000
	v_mov_b32_e32 v38, v35
	v_mov_b32_e32 v39, v35
	v_mov_b32_e32 v40, v35
	v_mov_b32_e32 v41, v35
	v_mov_b32_e32 v42, v35
	v_mov_b32_e32 v43, v35
	v_mov_b32_e32 v44, v35
	v_mov_b32_e32 v45, v35
	s_waitcnt vmcnt(57)
	v_mul_f32_e32 v22, 0xbfb8aa3b, v8
	s_waitcnt vmcnt(56)
	v_mul_f32_e32 v23, 0xbfb8aa3b, v9
	v_exp_f32_e32 v23, v23
	v_exp_f32_e32 v22, v22
	s_waitcnt vmcnt(55)
	v_mul_f32_e32 v24, 0xbfb8aa3b, v10
	s_waitcnt vmcnt(54)
	v_mul_f32_e32 v25, 0xbfb8aa3b, v11
	v_exp_f32_e32 v24, v24
	v_exp_f32_e32 v25, v25
	v_add_f32_e32 v23, 1.0, v23
	v_rcp_f32_e32 v23, v23
	s_waitcnt vmcnt(53)
	v_mul_f32_e32 v26, 0xbfb8aa3b, v12
	s_waitcnt vmcnt(52)
	v_mul_f32_e32 v27, 0xbfb8aa3b, v13
	v_exp_f32_e32 v27, v27
	v_add_f32_e32 v22, 1.0, v22
	v_exp_f32_e32 v26, v26
	v_rcp_f32_e32 v22, v22
	v_add_f32_e32 v24, 1.0, v24
	s_waitcnt vmcnt(51)
	v_mul_f32_e32 v28, 0xbfb8aa3b, v14
	v_add_f32_e32 v25, 1.0, v25
	v_rcp_f32_e32 v24, v24
	v_add_f32_e32 v27, 1.0, v27
	v_exp_f32_e32 v28, v28
	v_rcp_f32_e32 v25, v25
	v_mul_f32_e32 v9, v9, v23
	v_rcp_f32_e32 v23, v27
	v_add_f32_e32 v26, 1.0, v26
	v_mul_f32_e32 v8, v8, v22
	v_rcp_f32_e32 v22, v26
	v_mul_f32_e32 v10, v10, v24
	v_add_f32_e32 v26, 1.0, v28
	ds_write_b32 v3, v9 offset:16384
	v_mul_f32_e32 v11, v11, v25
	ds_write2_b32 v3, v8, v10 offset1:1
	v_mul_f32_e32 v10, v13, v23
	s_waitcnt vmcnt(50)
	v_mul_f32_e32 v29, 0xbfb8aa3b, v15
	v_rcp_f32_e32 v9, v26
	ds_write2_b32 v21, v11, v10 offset0:1 offset1:2
	s_waitcnt vmcnt(48)
	v_mul_f32_e32 v10, 0xbfb8aa3b, v17
	v_mul_f32_e32 v8, v12, v22
	v_exp_f32_e32 v12, v29
	v_exp_f32_e32 v10, v10
	v_mul_f32_e32 v9, v14, v9
	ds_write2_b32 v3, v8, v9 offset0:2 offset1:3
	v_add_f32_e32 v8, 1.0, v12
	v_add_f32_e32 v10, 1.0, v10
	v_rcp_f32_e32 v8, v8
	v_rcp_f32_e32 v10, v10
	s_waitcnt vmcnt(47)
	v_mul_f32_e32 v11, 0xbfb8aa3b, v18
	v_exp_f32_e32 v11, v11
	v_mul_f32_e32 v9, 0xbfb8aa3b, v16
	v_mul_f32_e32 v8, v15, v8
	v_mul_f32_e32 v10, v17, v10
	v_exp_f32_e32 v9, v9
	ds_write2_b32 v21, v8, v10 offset0:3 offset1:4
	v_add_f32_e32 v8, 1.0, v11
	s_waitcnt vmcnt(46)
	v_mul_f32_e32 v10, 0xbfb8aa3b, v19
	s_waitcnt vmcnt(45)
	v_mul_f32_e32 v11, 0xbfb8aa3b, v20
	v_exp_f32_e32 v10, v10
	v_exp_f32_e32 v11, v11
	v_add_f32_e32 v9, 1.0, v9
	v_rcp_f32_e32 v9, v9
	v_rcp_f32_e32 v8, v8
	v_add_f32_e32 v10, 1.0, v10
	v_add_f32_e32 v11, 1.0, v11
	s_waitcnt vmcnt(44)
	v_mul_f32_e32 v12, 0xbfb8aa3b, v6
	v_rcp_f32_e32 v10, v10
	v_rcp_f32_e32 v11, v11
	v_exp_f32_e32 v12, v12
	v_mul_f32_e32 v9, v16, v9
	v_mul_f32_e32 v8, v18, v8
	ds_write2_b32 v3, v9, v8 offset0:4 offset1:5
	v_mul_f32_e32 v8, v19, v10
	v_mul_f32_e32 v9, v20, v11
	v_add_f32_e32 v10, 1.0, v12
	s_waitcnt vmcnt(43)
	v_mul_f32_e32 v11, 0xbfb8aa3b, v7
	s_waitcnt vmcnt(42)
	v_mul_f32_e32 v12, 0xbfb8aa3b, v2
	v_rcp_f32_e32 v10, v10
	v_exp_f32_e32 v11, v11
	v_exp_f32_e32 v12, v12
	v_mul_f32_e32 v6, v6, v10
	v_add_f32_e32 v10, 1.0, v11
	v_add_f32_e32 v11, 1.0, v12
	v_rcp_f32_e32 v10, v10
	v_rcp_f32_e32 v11, v11
	ds_write2_b32 v21, v8, v6 offset0:5 offset1:6
	v_mul_f32_e32 v6, v7, v10
	v_mul_f32_e32 v2, v2, v11
	ds_write2_b32 v3, v9, v6 offset0:6 offset1:7
	ds_write_b32 v3, v2 offset:16412
	v_lshrrev_b32_e32 v2, 5, v1
	v_lshl_or_b32 v6, s99, 7, v2
	v_mad_u64_u32 v[2:3], s[24:25], v6, s1, v[4:5]
	v_lshl_add_u64 v[2:3], s[6:7], 2, v[2:3]
	v_lshl_add_u64 v[36:37], v[2:3], 0, v[34:35]
	v_lshl_add_u32 v49, v6, 5, 0
	s_mov_b32 s1, 0xc000
	s_mov_b32 s7, 0x24000
	s_mov_b32 s24, 0x30000
	s_mov_b32 s25, 0x3c000
	s_waitcnt lgkmcnt(0)
	s_barrier
	s_waitcnt vmcnt(38)
	global_load_dword v216, v[240:241], off nt
	v_lshl_add_u64 v[240:241], v[240:241], 0, s[96:97]
	global_load_dword v217, v[240:241], off nt
	v_lshl_add_u64 v[240:241], v[240:241], 0, s[96:97]
	global_load_dword v218, v[240:241], off nt
	v_lshl_add_u64 v[240:241], v[240:241], 0, s[96:97]
	global_load_dword v219, v[240:241], off nt
	v_lshl_add_u64 v[240:241], v[240:241], 0, s[96:97]
	global_load_dword v220, v[240:241], off nt
	v_lshl_add_u64 v[240:241], v[240:241], 0, s[96:97]
	global_load_dword v221, v[240:241], off nt
	v_lshl_add_u64 v[240:241], v[240:241], 0, s[96:97]
	global_load_dword v222, v[240:241], off nt
	v_lshl_add_u64 v[240:241], v[240:241], 0, s[96:97]
	global_load_dword v223, v[240:241], off nt
	v_lshl_add_u64 v[240:241], v[240:241], 0, s[96:97]
	global_load_dword v224, v[240:241], off nt
	v_lshl_add_u64 v[240:241], v[240:241], 0, s[96:97]
	global_load_dword v225, v[240:241], off nt
	v_lshl_add_u64 v[240:241], v[240:241], 0, s[96:97]
	global_load_dword v226, v[240:241], off nt
	v_lshl_add_u64 v[240:241], v[240:241], 0, s[96:97]
	global_load_dword v227, v[240:241], off nt
	v_lshl_add_u64 v[240:241], v[240:241], 0, s[96:97]
	global_load_dword v228, v[240:241], off nt
	v_lshl_add_u64 v[240:241], v[240:241], 0, s[96:97]
	global_load_dword v229, v[240:241], off nt
	v_lshl_add_u64 v[240:241], v[240:241], 0, s[96:97]
	global_load_dword v230, v[240:241], off nt
	v_lshl_add_u64 v[240:241], v[240:241], 0, s[96:97]
	global_load_dword v231, v[240:241], off nt
	v_lshl_add_u64 v[240:241], v[240:241], 0, s[96:97]
	global_load_dword v232, v[240:241], off nt
	v_lshl_add_u64 v[240:241], v[240:241], 0, s[96:97]
	global_load_dword v233, v[240:241], off nt
	v_lshl_add_u64 v[240:241], v[240:241], 0, s[96:97]
	global_load_dword v234, v[240:241], off nt
	v_lshl_add_u64 v[240:241], v[240:241], 0, s[96:97]
	global_load_dword v235, v[240:241], off nt
	v_lshl_add_u64 v[240:241], v[240:241], 0, s[96:97]
	global_load_dword v236, v[240:241], off nt
	v_lshl_add_u64 v[240:241], v[240:241], 0, s[96:97]
	global_load_dword v237, v[240:241], off nt
	v_lshl_add_u64 v[240:241], v[240:241], 0, s[96:97]
	global_load_dword v238, v[240:241], off nt
	v_lshl_add_u64 v[240:241], v[240:241], 0, s[96:97]
	global_load_dword v239, v[240:241], off nt
	ds_read_b128 v[6:9], v49 offset:0
	ds_read_b128 v[2:5], v49 offset:16
	ds_read_b128 v[14:17], v49 offset:64
	ds_read_b128 v[10:13], v49 offset:80
	ds_read_b128 v[22:25], v49 offset:128
	ds_read_b128 v[18:21], v49 offset:144
	ds_read_b128 v[26:29], v49 offset:192
	ds_read_b128 v[30:33], v49 offset:208
	ds_read_b128 v[50:53], v49 offset:256
	ds_read_b128 v[54:57], v49 offset:272
	ds_read_b128 v[58:61], v49 offset:320
	ds_read_b128 v[62:65], v49 offset:336
	ds_read_b128 v[66:69], v49 offset:384
	ds_read_b128 v[70:73], v49 offset:400
	ds_read_b128 v[74:77], v49 offset:448
	ds_read_b128 v[78:81], v49 offset:464
	ds_read_b128 v[82:85], v49 offset:512
	ds_read_b128 v[86:89], v49 offset:528
	ds_read_b128 v[90:93], v49 offset:576
	ds_read_b128 v[94:97], v49 offset:592
	ds_read_b128 v[98:101], v49 offset:640
	ds_read_b128 v[102:105], v49 offset:656
	ds_read_b128 v[106:109], v49 offset:704
	ds_read_b128 v[110:113], v49 offset:720
	ds_read_b128 v[114:117], v49 offset:768
	ds_read_b128 v[118:121], v49 offset:784
	ds_read_b128 v[122:125], v49 offset:832
	ds_read_b128 v[126:129], v49 offset:848
	ds_read_b128 v[130:133], v49 offset:896
	ds_read_b128 v[134:137], v49 offset:912
	ds_read_b128 v[138:141], v49 offset:960
	ds_read_b128 v[142:145], v49 offset:976
	v_add_u32_e32 v49, 0x400, v49
	s_waitcnt lgkmcnt(0)
	s_waitcnt vmcnt(63)
	v_pk_fma_f32 v[38:39], v[176:177], v[6:7], v[38:39] op_sel_hi:[0,1,1]
	v_pk_fma_f32 v[40:41], v[176:177], v[8:9], v[40:41] op_sel_hi:[0,1,1]
	v_pk_fma_f32 v[42:43], v[176:177], v[2:3], v[42:43] op_sel_hi:[0,1,1]
	v_pk_fma_f32 v[44:45], v[176:177], v[4:5], v[44:45] op_sel_hi:[0,1,1]
	s_waitcnt vmcnt(62)
	v_pk_fma_f32 v[38:39], v[176:177], v[14:15], v[38:39] op_sel:[1,0,0] op_sel_hi:[1,1,1]
	v_pk_fma_f32 v[40:41], v[176:177], v[16:17], v[40:41] op_sel:[1,0,0] op_sel_hi:[1,1,1]
	v_pk_fma_f32 v[42:43], v[176:177], v[10:11], v[42:43] op_sel:[1,0,0] op_sel_hi:[1,1,1]
	v_pk_fma_f32 v[44:45], v[176:177], v[12:13], v[44:45] op_sel:[1,0,0] op_sel_hi:[1,1,1]
	s_waitcnt vmcnt(61)
	v_pk_fma_f32 v[38:39], v[178:179], v[22:23], v[38:39] op_sel_hi:[0,1,1]
	v_pk_fma_f32 v[40:41], v[178:179], v[24:25], v[40:41] op_sel_hi:[0,1,1]
	v_pk_fma_f32 v[42:43], v[178:179], v[18:19], v[42:43] op_sel_hi:[0,1,1]
	v_pk_fma_f32 v[44:45], v[178:179], v[20:21], v[44:45] op_sel_hi:[0,1,1]
	s_waitcnt vmcnt(60)
	v_pk_fma_f32 v[38:39], v[178:179], v[26:27], v[38:39] op_sel:[1,0,0] op_sel_hi:[1,1,1]
	v_pk_fma_f32 v[40:41], v[178:179], v[28:29], v[40:41] op_sel:[1,0,0] op_sel_hi:[1,1,1]
	v_pk_fma_f32 v[42:43], v[178:179], v[30:31], v[42:43] op_sel:[1,0,0] op_sel_hi:[1,1,1]
	v_pk_fma_f32 v[44:45], v[178:179], v[32:33], v[44:45] op_sel:[1,0,0] op_sel_hi:[1,1,1]
	s_waitcnt vmcnt(59)
	v_pk_fma_f32 v[38:39], v[180:181], v[50:51], v[38:39] op_sel_hi:[0,1,1]
	v_pk_fma_f32 v[40:41], v[180:181], v[52:53], v[40:41] op_sel_hi:[0,1,1]
	v_pk_fma_f32 v[42:43], v[180:181], v[54:55], v[42:43] op_sel_hi:[0,1,1]
	v_pk_fma_f32 v[44:45], v[180:181], v[56:57], v[44:45] op_sel_hi:[0,1,1]
	s_waitcnt vmcnt(58)
	v_pk_fma_f32 v[38:39], v[180:181], v[58:59], v[38:39] op_sel:[1,0,0] op_sel_hi:[1,1,1]
	v_pk_fma_f32 v[40:41], v[180:181], v[60:61], v[40:41] op_sel:[1,0,0] op_sel_hi:[1,1,1]
	v_pk_fma_f32 v[42:43], v[180:181], v[62:63], v[42:43] op_sel:[1,0,0] op_sel_hi:[1,1,1]
	v_pk_fma_f32 v[44:45], v[180:181], v[64:65], v[44:45] op_sel:[1,0,0] op_sel_hi:[1,1,1]
	s_waitcnt vmcnt(57)
	v_pk_fma_f32 v[38:39], v[182:183], v[66:67], v[38:39] op_sel_hi:[0,1,1]
	v_pk_fma_f32 v[40:41], v[182:183], v[68:69], v[40:41] op_sel_hi:[0,1,1]
	v_pk_fma_f32 v[42:43], v[182:183], v[70:71], v[42:43] op_sel_hi:[0,1,1]
	v_pk_fma_f32 v[44:45], v[182:183], v[72:73], v[44:45] op_sel_hi:[0,1,1]
	s_waitcnt vmcnt(56)
	v_pk_fma_f32 v[38:39], v[182:183], v[74:75], v[38:39] op_sel:[1,0,0] op_sel_hi:[1,1,1]
	v_pk_fma_f32 v[40:41], v[182:183], v[76:77], v[40:41] op_sel:[1,0,0] op_sel_hi:[1,1,1]
	v_pk_fma_f32 v[42:43], v[182:183], v[78:79], v[42:43] op_sel:[1,0,0] op_sel_hi:[1,1,1]
	v_pk_fma_f32 v[44:45], v[182:183], v[80:81], v[44:45] op_sel:[1,0,0] op_sel_hi:[1,1,1]
	s_waitcnt vmcnt(55)
	v_pk_fma_f32 v[38:39], v[184:185], v[82:83], v[38:39] op_sel_hi:[0,1,1]
	v_pk_fma_f32 v[40:41], v[184:185], v[84:85], v[40:41] op_sel_hi:[0,1,1]
	v_pk_fma_f32 v[42:43], v[184:185], v[86:87], v[42:43] op_sel_hi:[0,1,1]
	v_pk_fma_f32 v[44:45], v[184:185], v[88:89], v[44:45] op_sel_hi:[0,1,1]
	s_waitcnt vmcnt(54)
	v_pk_fma_f32 v[38:39], v[184:185], v[90:91], v[38:39] op_sel:[1,0,0] op_sel_hi:[1,1,1]
	v_pk_fma_f32 v[40:41], v[184:185], v[92:93], v[40:41] op_sel:[1,0,0] op_sel_hi:[1,1,1]
	v_pk_fma_f32 v[42:43], v[184:185], v[94:95], v[42:43] op_sel:[1,0,0] op_sel_hi:[1,1,1]
	v_pk_fma_f32 v[44:45], v[184:185], v[96:97], v[44:45] op_sel:[1,0,0] op_sel_hi:[1,1,1]
	s_waitcnt vmcnt(53)
	v_pk_fma_f32 v[38:39], v[186:187], v[98:99], v[38:39] op_sel_hi:[0,1,1]
	v_pk_fma_f32 v[40:41], v[186:187], v[100:101], v[40:41] op_sel_hi:[0,1,1]
	v_pk_fma_f32 v[42:43], v[186:187], v[102:103], v[42:43] op_sel_hi:[0,1,1]
	v_pk_fma_f32 v[44:45], v[186:187], v[104:105], v[44:45] op_sel_hi:[0,1,1]
	s_waitcnt vmcnt(52)
	v_pk_fma_f32 v[38:39], v[186:187], v[106:107], v[38:39] op_sel:[1,0,0] op_sel_hi:[1,1,1]
	v_pk_fma_f32 v[40:41], v[186:187], v[108:109], v[40:41] op_sel:[1,0,0] op_sel_hi:[1,1,1]
	v_pk_fma_f32 v[42:43], v[186:187], v[110:111], v[42:43] op_sel:[1,0,0] op_sel_hi:[1,1,1]
	v_pk_fma_f32 v[44:45], v[186:187], v[112:113], v[44:45] op_sel:[1,0,0] op_sel_hi:[1,1,1]
	s_waitcnt vmcnt(51)
	v_pk_fma_f32 v[38:39], v[188:189], v[114:115], v[38:39] op_sel_hi:[0,1,1]
	v_pk_fma_f32 v[40:41], v[188:189], v[116:117], v[40:41] op_sel_hi:[0,1,1]
	v_pk_fma_f32 v[42:43], v[188:189], v[118:119], v[42:43] op_sel_hi:[0,1,1]
	v_pk_fma_f32 v[44:45], v[188:189], v[120:121], v[44:45] op_sel_hi:[0,1,1]
	s_waitcnt vmcnt(50)
	v_pk_fma_f32 v[38:39], v[188:189], v[122:123], v[38:39] op_sel:[1,0,0] op_sel_hi:[1,1,1]
	v_pk_fma_f32 v[40:41], v[188:189], v[124:125], v[40:41] op_sel:[1,0,0] op_sel_hi:[1,1,1]
	v_pk_fma_f32 v[42:43], v[188:189], v[126:127], v[42:43] op_sel:[1,0,0] op_sel_hi:[1,1,1]
	v_pk_fma_f32 v[44:45], v[188:189], v[128:129], v[44:45] op_sel:[1,0,0] op_sel_hi:[1,1,1]
	s_waitcnt vmcnt(49)
	v_pk_fma_f32 v[38:39], v[190:191], v[130:131], v[38:39] op_sel_hi:[0,1,1]
	v_pk_fma_f32 v[40:41], v[190:191], v[132:133], v[40:41] op_sel_hi:[0,1,1]
	v_pk_fma_f32 v[42:43], v[190:191], v[134:135], v[42:43] op_sel_hi:[0,1,1]
	v_pk_fma_f32 v[44:45], v[190:191], v[136:137], v[44:45] op_sel_hi:[0,1,1]
	s_waitcnt vmcnt(48)
	v_pk_fma_f32 v[38:39], v[190:191], v[138:139], v[38:39] op_sel:[1,0,0] op_sel_hi:[1,1,1]
	v_pk_fma_f32 v[40:41], v[190:191], v[140:141], v[40:41] op_sel:[1,0,0] op_sel_hi:[1,1,1]
	v_pk_fma_f32 v[42:43], v[190:191], v[142:143], v[42:43] op_sel:[1,0,0] op_sel_hi:[1,1,1]
	v_pk_fma_f32 v[44:45], v[190:191], v[144:145], v[44:45] op_sel:[1,0,0] op_sel_hi:[1,1,1]
	ds_read_b128 v[6:9], v49 offset:0
	ds_read_b128 v[2:5], v49 offset:16
	ds_read_b128 v[14:17], v49 offset:64
	ds_read_b128 v[10:13], v49 offset:80
	ds_read_b128 v[22:25], v49 offset:128
	ds_read_b128 v[18:21], v49 offset:144
	ds_read_b128 v[26:29], v49 offset:192
	ds_read_b128 v[30:33], v49 offset:208
	ds_read_b128 v[50:53], v49 offset:256
	ds_read_b128 v[54:57], v49 offset:272
	ds_read_b128 v[58:61], v49 offset:320
	ds_read_b128 v[62:65], v49 offset:336
	ds_read_b128 v[66:69], v49 offset:384
	ds_read_b128 v[70:73], v49 offset:400
	ds_read_b128 v[74:77], v49 offset:448
	ds_read_b128 v[78:81], v49 offset:464
	ds_read_b128 v[82:85], v49 offset:512
	ds_read_b128 v[86:89], v49 offset:528
	ds_read_b128 v[90:93], v49 offset:576
	ds_read_b128 v[94:97], v49 offset:592
	ds_read_b128 v[98:101], v49 offset:640
	ds_read_b128 v[102:105], v49 offset:656
	ds_read_b128 v[106:109], v49 offset:704
	ds_read_b128 v[110:113], v49 offset:720
	ds_read_b128 v[114:117], v49 offset:768
	ds_read_b128 v[118:121], v49 offset:784
	ds_read_b128 v[122:125], v49 offset:832
	ds_read_b128 v[126:129], v49 offset:848
	ds_read_b128 v[130:133], v49 offset:896
	ds_read_b128 v[134:137], v49 offset:912
	ds_read_b128 v[138:141], v49 offset:960
	ds_read_b128 v[142:145], v49 offset:976
	v_add_u32_e32 v49, 0x400, v49
	s_waitcnt lgkmcnt(0)
	s_waitcnt vmcnt(47)
	v_pk_fma_f32 v[38:39], v[192:193], v[6:7], v[38:39] op_sel_hi:[0,1,1]
	v_pk_fma_f32 v[40:41], v[192:193], v[8:9], v[40:41] op_sel_hi:[0,1,1]
	v_pk_fma_f32 v[42:43], v[192:193], v[2:3], v[42:43] op_sel_hi:[0,1,1]
	v_pk_fma_f32 v[44:45], v[192:193], v[4:5], v[44:45] op_sel_hi:[0,1,1]
	s_waitcnt vmcnt(46)
	v_pk_fma_f32 v[38:39], v[192:193], v[14:15], v[38:39] op_sel:[1,0,0] op_sel_hi:[1,1,1]
	v_pk_fma_f32 v[40:41], v[192:193], v[16:17], v[40:41] op_sel:[1,0,0] op_sel_hi:[1,1,1]
	v_pk_fma_f32 v[42:43], v[192:193], v[10:11], v[42:43] op_sel:[1,0,0] op_sel_hi:[1,1,1]
	v_pk_fma_f32 v[44:45], v[192:193], v[12:13], v[44:45] op_sel:[1,0,0] op_sel_hi:[1,1,1]
	s_waitcnt vmcnt(45)
	v_pk_fma_f32 v[38:39], v[194:195], v[22:23], v[38:39] op_sel_hi:[0,1,1]
	v_pk_fma_f32 v[40:41], v[194:195], v[24:25], v[40:41] op_sel_hi:[0,1,1]
	v_pk_fma_f32 v[42:43], v[194:195], v[18:19], v[42:43] op_sel_hi:[0,1,1]
	v_pk_fma_f32 v[44:45], v[194:195], v[20:21], v[44:45] op_sel_hi:[0,1,1]
	s_waitcnt vmcnt(44)
	v_pk_fma_f32 v[38:39], v[194:195], v[26:27], v[38:39] op_sel:[1,0,0] op_sel_hi:[1,1,1]
	v_pk_fma_f32 v[40:41], v[194:195], v[28:29], v[40:41] op_sel:[1,0,0] op_sel_hi:[1,1,1]
	v_pk_fma_f32 v[42:43], v[194:195], v[30:31], v[42:43] op_sel:[1,0,0] op_sel_hi:[1,1,1]
	v_pk_fma_f32 v[44:45], v[194:195], v[32:33], v[44:45] op_sel:[1,0,0] op_sel_hi:[1,1,1]
	s_waitcnt vmcnt(43)
	v_pk_fma_f32 v[38:39], v[196:197], v[50:51], v[38:39] op_sel_hi:[0,1,1]
	v_pk_fma_f32 v[40:41], v[196:197], v[52:53], v[40:41] op_sel_hi:[0,1,1]
	v_pk_fma_f32 v[42:43], v[196:197], v[54:55], v[42:43] op_sel_hi:[0,1,1]
	v_pk_fma_f32 v[44:45], v[196:197], v[56:57], v[44:45] op_sel_hi:[0,1,1]
	s_waitcnt vmcnt(42)
	v_pk_fma_f32 v[38:39], v[196:197], v[58:59], v[38:39] op_sel:[1,0,0] op_sel_hi:[1,1,1]
	v_pk_fma_f32 v[40:41], v[196:197], v[60:61], v[40:41] op_sel:[1,0,0] op_sel_hi:[1,1,1]
	v_pk_fma_f32 v[42:43], v[196:197], v[62:63], v[42:43] op_sel:[1,0,0] op_sel_hi:[1,1,1]
	v_pk_fma_f32 v[44:45], v[196:197], v[64:65], v[44:45] op_sel:[1,0,0] op_sel_hi:[1,1,1]
	s_waitcnt vmcnt(41)
	v_pk_fma_f32 v[38:39], v[198:199], v[66:67], v[38:39] op_sel_hi:[0,1,1]
	v_pk_fma_f32 v[40:41], v[198:199], v[68:69], v[40:41] op_sel_hi:[0,1,1]
	v_pk_fma_f32 v[42:43], v[198:199], v[70:71], v[42:43] op_sel_hi:[0,1,1]
	v_pk_fma_f32 v[44:45], v[198:199], v[72:73], v[44:45] op_sel_hi:[0,1,1]
	s_waitcnt vmcnt(40)
	v_pk_fma_f32 v[38:39], v[198:199], v[74:75], v[38:39] op_sel:[1,0,0] op_sel_hi:[1,1,1]
	v_pk_fma_f32 v[40:41], v[198:199], v[76:77], v[40:41] op_sel:[1,0,0] op_sel_hi:[1,1,1]
	v_pk_fma_f32 v[42:43], v[198:199], v[78:79], v[42:43] op_sel:[1,0,0] op_sel_hi:[1,1,1]
	v_pk_fma_f32 v[44:45], v[198:199], v[80:81], v[44:45] op_sel:[1,0,0] op_sel_hi:[1,1,1]
	s_waitcnt vmcnt(39)
	v_pk_fma_f32 v[38:39], v[200:201], v[82:83], v[38:39] op_sel_hi:[0,1,1]
	v_pk_fma_f32 v[40:41], v[200:201], v[84:85], v[40:41] op_sel_hi:[0,1,1]
	v_pk_fma_f32 v[42:43], v[200:201], v[86:87], v[42:43] op_sel_hi:[0,1,1]
	v_pk_fma_f32 v[44:45], v[200:201], v[88:89], v[44:45] op_sel_hi:[0,1,1]
	s_waitcnt vmcnt(38)
	v_pk_fma_f32 v[38:39], v[200:201], v[90:91], v[38:39] op_sel:[1,0,0] op_sel_hi:[1,1,1]
	v_pk_fma_f32 v[40:41], v[200:201], v[92:93], v[40:41] op_sel:[1,0,0] op_sel_hi:[1,1,1]
	v_pk_fma_f32 v[42:43], v[200:201], v[94:95], v[42:43] op_sel:[1,0,0] op_sel_hi:[1,1,1]
	v_pk_fma_f32 v[44:45], v[200:201], v[96:97], v[44:45] op_sel:[1,0,0] op_sel_hi:[1,1,1]
	s_waitcnt vmcnt(37)
	v_pk_fma_f32 v[38:39], v[202:203], v[98:99], v[38:39] op_sel_hi:[0,1,1]
	v_pk_fma_f32 v[40:41], v[202:203], v[100:101], v[40:41] op_sel_hi:[0,1,1]
	v_pk_fma_f32 v[42:43], v[202:203], v[102:103], v[42:43] op_sel_hi:[0,1,1]
	v_pk_fma_f32 v[44:45], v[202:203], v[104:105], v[44:45] op_sel_hi:[0,1,1]
	s_waitcnt vmcnt(36)
	v_pk_fma_f32 v[38:39], v[202:203], v[106:107], v[38:39] op_sel:[1,0,0] op_sel_hi:[1,1,1]
	v_pk_fma_f32 v[40:41], v[202:203], v[108:109], v[40:41] op_sel:[1,0,0] op_sel_hi:[1,1,1]
	v_pk_fma_f32 v[42:43], v[202:203], v[110:111], v[42:43] op_sel:[1,0,0] op_sel_hi:[1,1,1]
	v_pk_fma_f32 v[44:45], v[202:203], v[112:113], v[44:45] op_sel:[1,0,0] op_sel_hi:[1,1,1]
	s_waitcnt vmcnt(35)
	v_pk_fma_f32 v[38:39], v[204:205], v[114:115], v[38:39] op_sel_hi:[0,1,1]
	v_pk_fma_f32 v[40:41], v[204:205], v[116:117], v[40:41] op_sel_hi:[0,1,1]
	v_pk_fma_f32 v[42:43], v[204:205], v[118:119], v[42:43] op_sel_hi:[0,1,1]
	v_pk_fma_f32 v[44:45], v[204:205], v[120:121], v[44:45] op_sel_hi:[0,1,1]
	s_waitcnt vmcnt(34)
	v_pk_fma_f32 v[38:39], v[204:205], v[122:123], v[38:39] op_sel:[1,0,0] op_sel_hi:[1,1,1]
	v_pk_fma_f32 v[40:41], v[204:205], v[124:125], v[40:41] op_sel:[1,0,0] op_sel_hi:[1,1,1]
	v_pk_fma_f32 v[42:43], v[204:205], v[126:127], v[42:43] op_sel:[1,0,0] op_sel_hi:[1,1,1]
	v_pk_fma_f32 v[44:45], v[204:205], v[128:129], v[44:45] op_sel:[1,0,0] op_sel_hi:[1,1,1]
	s_waitcnt vmcnt(33)
	v_pk_fma_f32 v[38:39], v[206:207], v[130:131], v[38:39] op_sel_hi:[0,1,1]
	v_pk_fma_f32 v[40:41], v[206:207], v[132:133], v[40:41] op_sel_hi:[0,1,1]
	v_pk_fma_f32 v[42:43], v[206:207], v[134:135], v[42:43] op_sel_hi:[0,1,1]
	v_pk_fma_f32 v[44:45], v[206:207], v[136:137], v[44:45] op_sel_hi:[0,1,1]
	s_waitcnt vmcnt(32)
	v_pk_fma_f32 v[38:39], v[206:207], v[138:139], v[38:39] op_sel:[1,0,0] op_sel_hi:[1,1,1]
	v_pk_fma_f32 v[40:41], v[206:207], v[140:141], v[40:41] op_sel:[1,0,0] op_sel_hi:[1,1,1]
	v_pk_fma_f32 v[42:43], v[206:207], v[142:143], v[42:43] op_sel:[1,0,0] op_sel_hi:[1,1,1]
	v_pk_fma_f32 v[44:45], v[206:207], v[144:145], v[44:45] op_sel:[1,0,0] op_sel_hi:[1,1,1]
	ds_read_b128 v[6:9], v49 offset:0
	ds_read_b128 v[2:5], v49 offset:16
	ds_read_b128 v[14:17], v49 offset:64
	ds_read_b128 v[10:13], v49 offset:80
	ds_read_b128 v[22:25], v49 offset:128
	ds_read_b128 v[18:21], v49 offset:144
	ds_read_b128 v[26:29], v49 offset:192
	ds_read_b128 v[30:33], v49 offset:208
	ds_read_b128 v[50:53], v49 offset:256
	ds_read_b128 v[54:57], v49 offset:272
	ds_read_b128 v[58:61], v49 offset:320
	ds_read_b128 v[62:65], v49 offset:336
	ds_read_b128 v[66:69], v49 offset:384
	ds_read_b128 v[70:73], v49 offset:400
	ds_read_b128 v[74:77], v49 offset:448
	ds_read_b128 v[78:81], v49 offset:464
	ds_read_b128 v[82:85], v49 offset:512
	ds_read_b128 v[86:89], v49 offset:528
	ds_read_b128 v[90:93], v49 offset:576
	ds_read_b128 v[94:97], v49 offset:592
	ds_read_b128 v[98:101], v49 offset:640
	ds_read_b128 v[102:105], v49 offset:656
	ds_read_b128 v[106:109], v49 offset:704
	ds_read_b128 v[110:113], v49 offset:720
	ds_read_b128 v[114:117], v49 offset:768
	ds_read_b128 v[118:121], v49 offset:784
	ds_read_b128 v[122:125], v49 offset:832
	ds_read_b128 v[126:129], v49 offset:848
	ds_read_b128 v[130:133], v49 offset:896
	ds_read_b128 v[134:137], v49 offset:912
	ds_read_b128 v[138:141], v49 offset:960
	ds_read_b128 v[142:145], v49 offset:976
	v_add_u32_e32 v49, 0x400, v49
	s_waitcnt lgkmcnt(0)
	s_waitcnt vmcnt(31)
	v_pk_fma_f32 v[38:39], v[208:209], v[6:7], v[38:39] op_sel_hi:[0,1,1]
	v_pk_fma_f32 v[40:41], v[208:209], v[8:9], v[40:41] op_sel_hi:[0,1,1]
	v_pk_fma_f32 v[42:43], v[208:209], v[2:3], v[42:43] op_sel_hi:[0,1,1]
	v_pk_fma_f32 v[44:45], v[208:209], v[4:5], v[44:45] op_sel_hi:[0,1,1]
	s_waitcnt vmcnt(30)
	v_pk_fma_f32 v[38:39], v[208:209], v[14:15], v[38:39] op_sel:[1,0,0] op_sel_hi:[1,1,1]
	v_pk_fma_f32 v[40:41], v[208:209], v[16:17], v[40:41] op_sel:[1,0,0] op_sel_hi:[1,1,1]
	v_pk_fma_f32 v[42:43], v[208:209], v[10:11], v[42:43] op_sel:[1,0,0] op_sel_hi:[1,1,1]
	v_pk_fma_f32 v[44:45], v[208:209], v[12:13], v[44:45] op_sel:[1,0,0] op_sel_hi:[1,1,1]
	s_waitcnt vmcnt(29)
	v_pk_fma_f32 v[38:39], v[210:211], v[22:23], v[38:39] op_sel_hi:[0,1,1]
	v_pk_fma_f32 v[40:41], v[210:211], v[24:25], v[40:41] op_sel_hi:[0,1,1]
	v_pk_fma_f32 v[42:43], v[210:211], v[18:19], v[42:43] op_sel_hi:[0,1,1]
	v_pk_fma_f32 v[44:45], v[210:211], v[20:21], v[44:45] op_sel_hi:[0,1,1]
	s_waitcnt vmcnt(28)
	v_pk_fma_f32 v[38:39], v[210:211], v[26:27], v[38:39] op_sel:[1,0,0] op_sel_hi:[1,1,1]
	v_pk_fma_f32 v[40:41], v[210:211], v[28:29], v[40:41] op_sel:[1,0,0] op_sel_hi:[1,1,1]
	v_pk_fma_f32 v[42:43], v[210:211], v[30:31], v[42:43] op_sel:[1,0,0] op_sel_hi:[1,1,1]
	v_pk_fma_f32 v[44:45], v[210:211], v[32:33], v[44:45] op_sel:[1,0,0] op_sel_hi:[1,1,1]
	s_waitcnt vmcnt(27)
	v_pk_fma_f32 v[38:39], v[212:213], v[50:51], v[38:39] op_sel_hi:[0,1,1]
	v_pk_fma_f32 v[40:41], v[212:213], v[52:53], v[40:41] op_sel_hi:[0,1,1]
	v_pk_fma_f32 v[42:43], v[212:213], v[54:55], v[42:43] op_sel_hi:[0,1,1]
	v_pk_fma_f32 v[44:45], v[212:213], v[56:57], v[44:45] op_sel_hi:[0,1,1]
	s_waitcnt vmcnt(26)
	v_pk_fma_f32 v[38:39], v[212:213], v[58:59], v[38:39] op_sel:[1,0,0] op_sel_hi:[1,1,1]
	v_pk_fma_f32 v[40:41], v[212:213], v[60:61], v[40:41] op_sel:[1,0,0] op_sel_hi:[1,1,1]
	v_pk_fma_f32 v[42:43], v[212:213], v[62:63], v[42:43] op_sel:[1,0,0] op_sel_hi:[1,1,1]
	v_pk_fma_f32 v[44:45], v[212:213], v[64:65], v[44:45] op_sel:[1,0,0] op_sel_hi:[1,1,1]
	s_waitcnt vmcnt(25)
	v_pk_fma_f32 v[38:39], v[214:215], v[66:67], v[38:39] op_sel_hi:[0,1,1]
	v_pk_fma_f32 v[40:41], v[214:215], v[68:69], v[40:41] op_sel_hi:[0,1,1]
	v_pk_fma_f32 v[42:43], v[214:215], v[70:71], v[42:43] op_sel_hi:[0,1,1]
	v_pk_fma_f32 v[44:45], v[214:215], v[72:73], v[44:45] op_sel_hi:[0,1,1]
	s_waitcnt vmcnt(24)
	v_pk_fma_f32 v[38:39], v[214:215], v[74:75], v[38:39] op_sel:[1,0,0] op_sel_hi:[1,1,1]
	v_pk_fma_f32 v[40:41], v[214:215], v[76:77], v[40:41] op_sel:[1,0,0] op_sel_hi:[1,1,1]
	v_pk_fma_f32 v[42:43], v[214:215], v[78:79], v[42:43] op_sel:[1,0,0] op_sel_hi:[1,1,1]
	v_pk_fma_f32 v[44:45], v[214:215], v[80:81], v[44:45] op_sel:[1,0,0] op_sel_hi:[1,1,1]
	s_waitcnt vmcnt(23)
	v_pk_fma_f32 v[38:39], v[216:217], v[82:83], v[38:39] op_sel_hi:[0,1,1]
	v_pk_fma_f32 v[40:41], v[216:217], v[84:85], v[40:41] op_sel_hi:[0,1,1]
	v_pk_fma_f32 v[42:43], v[216:217], v[86:87], v[42:43] op_sel_hi:[0,1,1]
	v_pk_fma_f32 v[44:45], v[216:217], v[88:89], v[44:45] op_sel_hi:[0,1,1]
	s_waitcnt vmcnt(22)
	v_pk_fma_f32 v[38:39], v[216:217], v[90:91], v[38:39] op_sel:[1,0,0] op_sel_hi:[1,1,1]
	v_pk_fma_f32 v[40:41], v[216:217], v[92:93], v[40:41] op_sel:[1,0,0] op_sel_hi:[1,1,1]
	v_pk_fma_f32 v[42:43], v[216:217], v[94:95], v[42:43] op_sel:[1,0,0] op_sel_hi:[1,1,1]
	v_pk_fma_f32 v[44:45], v[216:217], v[96:97], v[44:45] op_sel:[1,0,0] op_sel_hi:[1,1,1]
	s_waitcnt vmcnt(21)
	v_pk_fma_f32 v[38:39], v[218:219], v[98:99], v[38:39] op_sel_hi:[0,1,1]
	v_pk_fma_f32 v[40:41], v[218:219], v[100:101], v[40:41] op_sel_hi:[0,1,1]
	v_pk_fma_f32 v[42:43], v[218:219], v[102:103], v[42:43] op_sel_hi:[0,1,1]
	v_pk_fma_f32 v[44:45], v[218:219], v[104:105], v[44:45] op_sel_hi:[0,1,1]
	s_waitcnt vmcnt(20)
	v_pk_fma_f32 v[38:39], v[218:219], v[106:107], v[38:39] op_sel:[1,0,0] op_sel_hi:[1,1,1]
	v_pk_fma_f32 v[40:41], v[218:219], v[108:109], v[40:41] op_sel:[1,0,0] op_sel_hi:[1,1,1]
	v_pk_fma_f32 v[42:43], v[218:219], v[110:111], v[42:43] op_sel:[1,0,0] op_sel_hi:[1,1,1]
	v_pk_fma_f32 v[44:45], v[218:219], v[112:113], v[44:45] op_sel:[1,0,0] op_sel_hi:[1,1,1]
	s_waitcnt vmcnt(19)
	v_pk_fma_f32 v[38:39], v[220:221], v[114:115], v[38:39] op_sel_hi:[0,1,1]
	v_pk_fma_f32 v[40:41], v[220:221], v[116:117], v[40:41] op_sel_hi:[0,1,1]
	v_pk_fma_f32 v[42:43], v[220:221], v[118:119], v[42:43] op_sel_hi:[0,1,1]
	v_pk_fma_f32 v[44:45], v[220:221], v[120:121], v[44:45] op_sel_hi:[0,1,1]
	s_waitcnt vmcnt(18)
	v_pk_fma_f32 v[38:39], v[220:221], v[122:123], v[38:39] op_sel:[1,0,0] op_sel_hi:[1,1,1]
	v_pk_fma_f32 v[40:41], v[220:221], v[124:125], v[40:41] op_sel:[1,0,0] op_sel_hi:[1,1,1]
	v_pk_fma_f32 v[42:43], v[220:221], v[126:127], v[42:43] op_sel:[1,0,0] op_sel_hi:[1,1,1]
	v_pk_fma_f32 v[44:45], v[220:221], v[128:129], v[44:45] op_sel:[1,0,0] op_sel_hi:[1,1,1]
	s_waitcnt vmcnt(17)
	v_pk_fma_f32 v[38:39], v[222:223], v[130:131], v[38:39] op_sel_hi:[0,1,1]
	v_pk_fma_f32 v[40:41], v[222:223], v[132:133], v[40:41] op_sel_hi:[0,1,1]
	v_pk_fma_f32 v[42:43], v[222:223], v[134:135], v[42:43] op_sel_hi:[0,1,1]
	v_pk_fma_f32 v[44:45], v[222:223], v[136:137], v[44:45] op_sel_hi:[0,1,1]
	s_waitcnt vmcnt(16)
	v_pk_fma_f32 v[38:39], v[222:223], v[138:139], v[38:39] op_sel:[1,0,0] op_sel_hi:[1,1,1]
	v_pk_fma_f32 v[40:41], v[222:223], v[140:141], v[40:41] op_sel:[1,0,0] op_sel_hi:[1,1,1]
	v_pk_fma_f32 v[42:43], v[222:223], v[142:143], v[42:43] op_sel:[1,0,0] op_sel_hi:[1,1,1]
	v_pk_fma_f32 v[44:45], v[222:223], v[144:145], v[44:45] op_sel:[1,0,0] op_sel_hi:[1,1,1]
	ds_read_b128 v[6:9], v49 offset:0
	ds_read_b128 v[2:5], v49 offset:16
	ds_read_b128 v[14:17], v49 offset:64
	ds_read_b128 v[10:13], v49 offset:80
	ds_read_b128 v[22:25], v49 offset:128
	ds_read_b128 v[18:21], v49 offset:144
	ds_read_b128 v[26:29], v49 offset:192
	ds_read_b128 v[30:33], v49 offset:208
	ds_read_b128 v[50:53], v49 offset:256
	ds_read_b128 v[54:57], v49 offset:272
	ds_read_b128 v[58:61], v49 offset:320
	ds_read_b128 v[62:65], v49 offset:336
	ds_read_b128 v[66:69], v49 offset:384
	ds_read_b128 v[70:73], v49 offset:400
	ds_read_b128 v[74:77], v49 offset:448
	ds_read_b128 v[78:81], v49 offset:464
	ds_read_b128 v[82:85], v49 offset:512
	ds_read_b128 v[86:89], v49 offset:528
	ds_read_b128 v[90:93], v49 offset:576
	ds_read_b128 v[94:97], v49 offset:592
	ds_read_b128 v[98:101], v49 offset:640
	ds_read_b128 v[102:105], v49 offset:656
	ds_read_b128 v[106:109], v49 offset:704
	ds_read_b128 v[110:113], v49 offset:720
	ds_read_b128 v[114:117], v49 offset:768
	ds_read_b128 v[118:121], v49 offset:784
	ds_read_b128 v[122:125], v49 offset:832
	ds_read_b128 v[126:129], v49 offset:848
	ds_read_b128 v[130:133], v49 offset:896
	ds_read_b128 v[134:137], v49 offset:912
	ds_read_b128 v[138:141], v49 offset:960
	ds_read_b128 v[142:145], v49 offset:976
	v_add_u32_e32 v49, 0x400, v49
	s_waitcnt lgkmcnt(0)
	s_waitcnt vmcnt(15)
	v_pk_fma_f32 v[38:39], v[224:225], v[6:7], v[38:39] op_sel_hi:[0,1,1]
	v_pk_fma_f32 v[40:41], v[224:225], v[8:9], v[40:41] op_sel_hi:[0,1,1]
	v_pk_fma_f32 v[42:43], v[224:225], v[2:3], v[42:43] op_sel_hi:[0,1,1]
	v_pk_fma_f32 v[44:45], v[224:225], v[4:5], v[44:45] op_sel_hi:[0,1,1]
	s_waitcnt vmcnt(14)
	v_pk_fma_f32 v[38:39], v[224:225], v[14:15], v[38:39] op_sel:[1,0,0] op_sel_hi:[1,1,1]
	v_pk_fma_f32 v[40:41], v[224:225], v[16:17], v[40:41] op_sel:[1,0,0] op_sel_hi:[1,1,1]
	v_pk_fma_f32 v[42:43], v[224:225], v[10:11], v[42:43] op_sel:[1,0,0] op_sel_hi:[1,1,1]
	v_pk_fma_f32 v[44:45], v[224:225], v[12:13], v[44:45] op_sel:[1,0,0] op_sel_hi:[1,1,1]
	s_waitcnt vmcnt(13)
	v_pk_fma_f32 v[38:39], v[226:227], v[22:23], v[38:39] op_sel_hi:[0,1,1]
	v_pk_fma_f32 v[40:41], v[226:227], v[24:25], v[40:41] op_sel_hi:[0,1,1]
	v_pk_fma_f32 v[42:43], v[226:227], v[18:19], v[42:43] op_sel_hi:[0,1,1]
	v_pk_fma_f32 v[44:45], v[226:227], v[20:21], v[44:45] op_sel_hi:[0,1,1]
	s_waitcnt vmcnt(12)
	v_pk_fma_f32 v[38:39], v[226:227], v[26:27], v[38:39] op_sel:[1,0,0] op_sel_hi:[1,1,1]
	v_pk_fma_f32 v[40:41], v[226:227], v[28:29], v[40:41] op_sel:[1,0,0] op_sel_hi:[1,1,1]
	v_pk_fma_f32 v[42:43], v[226:227], v[30:31], v[42:43] op_sel:[1,0,0] op_sel_hi:[1,1,1]
	v_pk_fma_f32 v[44:45], v[226:227], v[32:33], v[44:45] op_sel:[1,0,0] op_sel_hi:[1,1,1]
	s_waitcnt vmcnt(11)
	v_pk_fma_f32 v[38:39], v[228:229], v[50:51], v[38:39] op_sel_hi:[0,1,1]
	v_pk_fma_f32 v[40:41], v[228:229], v[52:53], v[40:41] op_sel_hi:[0,1,1]
	v_pk_fma_f32 v[42:43], v[228:229], v[54:55], v[42:43] op_sel_hi:[0,1,1]
	v_pk_fma_f32 v[44:45], v[228:229], v[56:57], v[44:45] op_sel_hi:[0,1,1]
	s_waitcnt vmcnt(10)
	v_pk_fma_f32 v[38:39], v[228:229], v[58:59], v[38:39] op_sel:[1,0,0] op_sel_hi:[1,1,1]
	v_pk_fma_f32 v[40:41], v[228:229], v[60:61], v[40:41] op_sel:[1,0,0] op_sel_hi:[1,1,1]
	v_pk_fma_f32 v[42:43], v[228:229], v[62:63], v[42:43] op_sel:[1,0,0] op_sel_hi:[1,1,1]
	v_pk_fma_f32 v[44:45], v[228:229], v[64:65], v[44:45] op_sel:[1,0,0] op_sel_hi:[1,1,1]
	s_waitcnt vmcnt(9)
	v_pk_fma_f32 v[38:39], v[230:231], v[66:67], v[38:39] op_sel_hi:[0,1,1]
	v_pk_fma_f32 v[40:41], v[230:231], v[68:69], v[40:41] op_sel_hi:[0,1,1]
	v_pk_fma_f32 v[42:43], v[230:231], v[70:71], v[42:43] op_sel_hi:[0,1,1]
	v_pk_fma_f32 v[44:45], v[230:231], v[72:73], v[44:45] op_sel_hi:[0,1,1]
	s_waitcnt vmcnt(8)
	v_pk_fma_f32 v[38:39], v[230:231], v[74:75], v[38:39] op_sel:[1,0,0] op_sel_hi:[1,1,1]
	v_pk_fma_f32 v[40:41], v[230:231], v[76:77], v[40:41] op_sel:[1,0,0] op_sel_hi:[1,1,1]
	v_pk_fma_f32 v[42:43], v[230:231], v[78:79], v[42:43] op_sel:[1,0,0] op_sel_hi:[1,1,1]
	v_pk_fma_f32 v[44:45], v[230:231], v[80:81], v[44:45] op_sel:[1,0,0] op_sel_hi:[1,1,1]
	s_waitcnt vmcnt(7)
	v_pk_fma_f32 v[38:39], v[232:233], v[82:83], v[38:39] op_sel_hi:[0,1,1]
	v_pk_fma_f32 v[40:41], v[232:233], v[84:85], v[40:41] op_sel_hi:[0,1,1]
	v_pk_fma_f32 v[42:43], v[232:233], v[86:87], v[42:43] op_sel_hi:[0,1,1]
	v_pk_fma_f32 v[44:45], v[232:233], v[88:89], v[44:45] op_sel_hi:[0,1,1]
	s_waitcnt vmcnt(6)
	v_pk_fma_f32 v[38:39], v[232:233], v[90:91], v[38:39] op_sel:[1,0,0] op_sel_hi:[1,1,1]
	v_pk_fma_f32 v[40:41], v[232:233], v[92:93], v[40:41] op_sel:[1,0,0] op_sel_hi:[1,1,1]
	v_pk_fma_f32 v[42:43], v[232:233], v[94:95], v[42:43] op_sel:[1,0,0] op_sel_hi:[1,1,1]
	v_pk_fma_f32 v[44:45], v[232:233], v[96:97], v[44:45] op_sel:[1,0,0] op_sel_hi:[1,1,1]
	s_waitcnt vmcnt(5)
	v_pk_fma_f32 v[38:39], v[234:235], v[98:99], v[38:39] op_sel_hi:[0,1,1]
	v_pk_fma_f32 v[40:41], v[234:235], v[100:101], v[40:41] op_sel_hi:[0,1,1]
	v_pk_fma_f32 v[42:43], v[234:235], v[102:103], v[42:43] op_sel_hi:[0,1,1]
	v_pk_fma_f32 v[44:45], v[234:235], v[104:105], v[44:45] op_sel_hi:[0,1,1]
	s_waitcnt vmcnt(4)
	v_pk_fma_f32 v[38:39], v[234:235], v[106:107], v[38:39] op_sel:[1,0,0] op_sel_hi:[1,1,1]
	v_pk_fma_f32 v[40:41], v[234:235], v[108:109], v[40:41] op_sel:[1,0,0] op_sel_hi:[1,1,1]
	v_pk_fma_f32 v[42:43], v[234:235], v[110:111], v[42:43] op_sel:[1,0,0] op_sel_hi:[1,1,1]
	v_pk_fma_f32 v[44:45], v[234:235], v[112:113], v[44:45] op_sel:[1,0,0] op_sel_hi:[1,1,1]
	s_waitcnt vmcnt(3)
	v_pk_fma_f32 v[38:39], v[236:237], v[114:115], v[38:39] op_sel_hi:[0,1,1]
	v_pk_fma_f32 v[40:41], v[236:237], v[116:117], v[40:41] op_sel_hi:[0,1,1]
	v_pk_fma_f32 v[42:43], v[236:237], v[118:119], v[42:43] op_sel_hi:[0,1,1]
	v_pk_fma_f32 v[44:45], v[236:237], v[120:121], v[44:45] op_sel_hi:[0,1,1]
	s_waitcnt vmcnt(2)
	v_pk_fma_f32 v[38:39], v[236:237], v[122:123], v[38:39] op_sel:[1,0,0] op_sel_hi:[1,1,1]
	v_pk_fma_f32 v[40:41], v[236:237], v[124:125], v[40:41] op_sel:[1,0,0] op_sel_hi:[1,1,1]
	v_pk_fma_f32 v[42:43], v[236:237], v[126:127], v[42:43] op_sel:[1,0,0] op_sel_hi:[1,1,1]
	v_pk_fma_f32 v[44:45], v[236:237], v[128:129], v[44:45] op_sel:[1,0,0] op_sel_hi:[1,1,1]
	s_waitcnt vmcnt(1)
	v_pk_fma_f32 v[38:39], v[238:239], v[130:131], v[38:39] op_sel_hi:[0,1,1]
	v_pk_fma_f32 v[40:41], v[238:239], v[132:133], v[40:41] op_sel_hi:[0,1,1]
	v_pk_fma_f32 v[42:43], v[238:239], v[134:135], v[42:43] op_sel_hi:[0,1,1]
	v_pk_fma_f32 v[44:45], v[238:239], v[136:137], v[44:45] op_sel_hi:[0,1,1]
	s_waitcnt vmcnt(0)
	v_pk_fma_f32 v[38:39], v[238:239], v[138:139], v[38:39] op_sel:[1,0,0] op_sel_hi:[1,1,1]
	v_pk_fma_f32 v[40:41], v[238:239], v[140:141], v[40:41] op_sel:[1,0,0] op_sel_hi:[1,1,1]
	v_pk_fma_f32 v[42:43], v[238:239], v[142:143], v[42:43] op_sel:[1,0,0] op_sel_hi:[1,1,1]
	v_pk_fma_f32 v[44:45], v[238:239], v[144:145], v[44:45] op_sel:[1,0,0] op_sel_hi:[1,1,1]
	v_mbcnt_lo_u32_b32 v2, -1, 0
	v_mbcnt_hi_u32_b32 v2, -1, v2
	v_and_b32_e32 v4, 64, v2
	v_xor_b32_e32 v3, 32, v2
	v_add_u32_e32 v4, 64, v4
	v_cmp_lt_i32_e32 vcc, v3, v4
	s_nop 1
	v_cndmask_b32_e32 v2, v2, v3, vcc
	v_lshlrev_b32_e32 v9, 2, v2
	ds_bpermute_b32 v2, v9, v38
	ds_bpermute_b32 v3, v9, v39
	ds_bpermute_b32 v4, v9, v40
	ds_bpermute_b32 v5, v9, v41
	ds_bpermute_b32 v6, v9, v42
	ds_bpermute_b32 v7, v9, v43
	ds_bpermute_b32 v8, v9, v44
	ds_bpermute_b32 v9, v9, v45
	v_cmp_gt_u32_e32 vcc, 32, v1
	s_and_saveexec_b64 s[38:39], vcc
	s_cbranch_execz .LBB0_17
	s_lshl_b32 s1, s99, 10
	s_add_i32 s1, s1, 0
	v_lshl_add_u32 v10, v1, 2, s1
	s_waitcnt lgkmcnt(6)
	v_add_f32_e32 v3, v39, v3
	v_add_f32_e32 v2, v38, v2
	v_add_u32_e32 v10, 0x8000, v10
	s_waitcnt lgkmcnt(0)
	v_add_f32_e32 v9, v45, v9
	v_add_f32_e32 v8, v44, v8
	v_add_f32_e32 v7, v43, v7
	v_add_f32_e32 v6, v42, v6
	v_add_f32_e32 v5, v41, v5
	v_add_f32_e32 v4, v40, v4
	ds_write2_b32 v10, v2, v3 offset1:32
	ds_write2_b32 v10, v4, v5 offset0:64 offset1:96
	ds_write2_b32 v10, v6, v7 offset0:128 offset1:160
	ds_write2_b32 v10, v8, v9 offset0:192 offset1:224
